# P0 w_up transpose: items dealt so a workgroup's 8 waves write 1 KB contiguous runs of the bf16 copy (8 consecutive k-blocks of one column block), plus 8 loads in flight
# speedup vs baseline: 1.0030x; 1.0030x over previous
.LBB0_19:
	s_andn2_b64 vcc, exec, s[4:5]
	s_cbranch_vccnz .LBB0_38
	s_add_i32 s0, s28, 0xa000
	s_lshr_b32 s0, s0, 3
	s_and_b32 s17, s0, 0xe00
	s_and_b32 s0, s28, 7
	s_lshl_b32 s0, s0, 6
	s_or_b32 s17, s17, s0
	s_lshl_b32 s16, s28, 2
	s_and_b32 s16, s16, 0x3fe0
	s_lshl_b32 s0, s16, 2
	v_or_b32_e32 v6, s17, v1
	v_lshl_add_u64 v[40:41], v[18:19], 0, s[0:1]
	v_lshlrev_b32_e32 v14, 16, v6
	v_add_lshl_u32 v39, s17, v1, 2
	v_lshl_add_u64 v[4:5], v[40:41], 0, v[14:15]
	global_load_dwordx4 v[4:7], v[4:5], off
	v_or_b32_sdwa v14, s17, v17 dst_sel:WORD_1 dst_unused:UNUSED_PAD src0_sel:DWORD src1_sel:DWORD
	s_nop 0
	v_lshl_add_u64 v[8:9], v[40:41], 0, v[14:15]
	global_load_dwordx4 v[8:11], v[8:9], off
	v_or_b32_sdwa v14, s17, v42 dst_sel:WORD_1 dst_unused:UNUSED_PAD src0_sel:DWORD src1_sel:DWORD
	s_nop 0
	v_lshl_add_u64 v[60:61], v[40:41], 0, v[14:15]
	global_load_dwordx4 v[60:63], v[60:61], off
	v_or_b32_sdwa v14, s17, v43 dst_sel:WORD_1 dst_unused:UNUSED_PAD src0_sel:DWORD src1_sel:DWORD
	s_nop 0
	v_lshl_add_u64 v[64:65], v[40:41], 0, v[14:15]
	global_load_dwordx4 v[64:67], v[64:65], off
	v_or_b32_sdwa v14, s17, v44 dst_sel:WORD_1 dst_unused:UNUSED_PAD src0_sel:DWORD src1_sel:DWORD
	s_nop 0
	v_lshl_add_u64 v[68:69], v[40:41], 0, v[14:15]
	global_load_dwordx4 v[68:71], v[68:69], off
	v_or_b32_sdwa v14, s17, v45 dst_sel:WORD_1 dst_unused:UNUSED_PAD src0_sel:DWORD src1_sel:DWORD
	s_nop 0
	v_lshl_add_u64 v[72:73], v[40:41], 0, v[14:15]
	global_load_dwordx4 v[72:75], v[72:73], off
	v_or_b32_sdwa v14, s17, v46 dst_sel:WORD_1 dst_unused:UNUSED_PAD src0_sel:DWORD src1_sel:DWORD
	s_nop 0
	v_lshl_add_u64 v[76:77], v[40:41], 0, v[14:15]
	global_load_dwordx4 v[76:79], v[76:77], off
	v_or_b32_sdwa v14, s17, v47 dst_sel:WORD_1 dst_unused:UNUSED_PAD src0_sel:DWORD src1_sel:DWORD
	s_nop 0
	v_lshl_add_u64 v[80:81], v[40:41], 0, v[14:15]
	global_load_dwordx4 v[80:83], v[80:81], off
	s_and_b64 vcc, exec, s[12:13]
	s_cbranch_vccz .Lwup_noscale
	v_readlane_b32 s46, v249, 30
	v_readlane_b32 s47, v249, 31
	v_readlane_b32 s36, v249, 20
	v_readlane_b32 s37, v249, 21
	v_readlane_b32 s38, v249, 22
	v_readlane_b32 s39, v249, 23
	v_readlane_b32 s40, v249, 24
	v_readlane_b32 s41, v249, 25
	v_readlane_b32 s42, v249, 26
	v_readlane_b32 s43, v249, 27
	v_readlane_b32 s44, v249, 28
	v_readlane_b32 s45, v249, 29
	v_readlane_b32 s48, v249, 32
	v_readlane_b32 s49, v249, 33
	v_readlane_b32 s50, v249, 34
	v_readlane_b32 s51, v249, 35
	global_load_dword v2, v39, s[46:47]
	s_nop 0
	global_load_dword v3, v39, s[46:47] offset:32
	s_nop 0
	global_load_dword v12, v39, s[46:47] offset:64
	s_nop 0
	global_load_dword v13, v39, s[46:47] offset:96
	s_nop 0
	global_load_dword v14, v39, s[46:47] offset:128
	s_nop 0
	global_load_dword v40, v39, s[46:47] offset:160
	s_nop 0
	global_load_dword v41, v39, s[46:47] offset:192
	s_nop 0
	global_load_dword v39, v39, s[46:47] offset:224
	s_waitcnt vmcnt(0)
	v_mul_f32_e32 v4, v2, v4
	v_mul_f32_e32 v5, v2, v5
	v_mul_f32_e32 v6, v2, v6
	v_mul_f32_e32 v7, v2, v7
	v_mul_f32_e32 v8, v3, v8
	v_mul_f32_e32 v9, v3, v9
	v_mul_f32_e32 v10, v3, v10
	v_mul_f32_e32 v11, v3, v11
	v_mul_f32_e32 v60, v12, v60
	v_mul_f32_e32 v61, v12, v61
	v_mul_f32_e32 v62, v12, v62
	v_mul_f32_e32 v63, v12, v63
	v_mul_f32_e32 v64, v13, v64
	v_mul_f32_e32 v65, v13, v65
	v_mul_f32_e32 v66, v13, v66
	v_mul_f32_e32 v67, v13, v67
	v_mul_f32_e32 v68, v14, v68
	v_mul_f32_e32 v69, v14, v69
	v_mul_f32_e32 v70, v14, v70
	v_mul_f32_e32 v71, v14, v71
	v_mul_f32_e32 v72, v40, v72
	v_mul_f32_e32 v73, v40, v73
	v_mul_f32_e32 v74, v40, v74
	v_mul_f32_e32 v75, v40, v75
	v_mul_f32_e32 v76, v41, v76
	v_mul_f32_e32 v77, v41, v77
	v_mul_f32_e32 v78, v41, v78
	v_mul_f32_e32 v79, v41, v79
	v_mul_f32_e32 v80, v39, v80
	v_mul_f32_e32 v81, v39, v81
	v_mul_f32_e32 v82, v39, v82
	v_mul_f32_e32 v83, v39, v83
